# up GEMM: first K-iteration of every unit peeled; its first MFMA per accumulator takes C=0 so the 128 v_mov accumulator clears per unit are gone
# speedup vs baseline: 1.2683x; 1.0036x over previous
; #define PG8_STAGE(bufoff, gbase, voff) do { _Pragma("unroll") for (int _i = 0; _i < 2; ++_i) \
;         __builtin_amdgcn_global_load_lds((const unsigned*)((const char*)(gbase) + (voff)[_i]), (PG8_LAS unsigned*)(lds + (bufoff) + ldsw + _i * 8192), 16, 0, 0); } while (0)
; #define PG8_LDA(dst, b, h) do { _Pragma("unroll") for (int m = 0; m < 4; ++m) _Pragma("unroll") for (int k = 0; k < 2; ++k) dst[m][k] = *(const PG8_LAS bf16x8*)(lds + PG8_SA(b, h) + aoff + m * 2048 + k * 1024); } while (0)
; #define PG8_LDB(dst, b, h) do { _Pragma("unroll") for (int n = 0; n < 2; ++n) _Pragma("unroll") for (int k = 0; k < 2; ++k) dst[n][k] = *(const PG8_LAS bf16x8*)(lds + PG8_SB(b, h) + boff + n * 2048 + k * 1024); } while (0)
; #define PG8_MMA(ai, bj, At, Bt) do { __builtin_amdgcn_s_setprio(1); _Pragma("unroll") for (int m = 0; m < 4; ++m) _Pragma("unroll") for (int n = 0; n < 2; ++n) _Pragma("unroll") for (int k = 0; k < 2; ++k) \
;         acc[ai][bj][m][n] = __builtin_amdgcn_mfma_f32_16x16x32_bf16(Bt[n][k], At[m][k], acc[ai][bj][m][n], 0, 0, 0); __builtin_amdgcn_s_setprio(0); } while (0)
; #define PG8_BAR __builtin_amdgcn_s_barrier()
; template <class Epi, class Sched, bool ALIGN_EPI = false, bool SP2 = false>
; __device__ __forceinline__ void gemm_phase(PG8_LAS unsigned char* lds, const Gemm g, const Sched& S, const Epi& E) {
;     ...
;         const bool has_next = S.next(ui + 1, nxt);
;         const char* nA = has_next ? (const char*)g.A + (size_t)nxt.pm * tstep : cA; const char* nB = has_next ? (const char*)g.Bt + (size_t)nxt.pn * tstep : cB;
;         for (int t = 0; t < nt; t += 2) {
;             const bool last = (t == nt - 2);
;             const char* a1 = cA + (size_t)(t + 1) * kstep;
;             const char* a2 = last ? nA : cA + (size_t)(t + 2) * kstep; const char* b2 = last ? nB : cB + (size_t)(t + 2) * kstep;
;             const char* a3 = a2 + kstep; const char* b3 = b2 + kstep;
;             if (last && has_next) S.a_ready(nxt);
;             if constexpr (SP2) {
;             PG8_LDB(B0, 0, 0); PG8_LDB(B1, 0, 1); PG8_SCHED; PG8_LDA(At, 0, 0); PG8_STAGE(PG8_SA(1, 1), a1 + hstep, voffA);
;             PG8_WAIT_V(8); PG8_WAIT_L(0); PG8_BAR; PG8_MMA(0, 0, At, B0); PG8_MMA(0, 1, At, B1); PG8_BAR; PG8_SCHED;
;             PG8_LDA(At, 0, 1); PG8_STAGE(PG8_SB(0, 0), b2, voffB); PG8_STAGE(PG8_SB(0, 1), b2 + hstep, voffB); PG8_STAGE(PG8_SA(0, 0), a2, voffA);
.LBB0_445:
	s_ashr_i32 s7, s6, 31
	s_lshl_b64 s[10:11], s[6:7], 19
	s_add_u32 s10, s23, s10
	s_addc_u32 s11, s24, s11
	s_and_b64 s[12:13], s[8:9], exec
	s_cselect_b32 s7, s11, s15
	s_cselect_b32 s49, s10, s14
	s_ashr_i32 s5, s4, 31
	s_lshl_b64 s[12:13], s[4:5], 19
	s_add_u32 s12, s25, s12
	s_addc_u32 s13, s26, s13
	s_and_b64 s[18:19], s[8:9], exec
	s_cselect_b32 s5, s13, s17
	s_cselect_b32 s50, s12, s16
	s_add_u32 s14, s14, 0x40080
	s_addc_u32 s15, s15, 0
	s_add_u32 s51, s16, 0x100
	s_addc_u32 s52, s17, 0
	s_mov_b32 s53, -2
.Lup_peel:
	v_or_b32_e32 v140, 0x10000, v166
	v_add_u32_e32 v162, 0x10400, v166
	ds_read_b128 v[140:143], v140
	ds_read_b128 v[168:171], v162
	v_add_u32_e32 v162, 0x10800, v166
	v_add_u32_e32 v163, 0x10c00, v166
	ds_read_b128 v[172:175], v162
	ds_read_b128 v[176:179], v163
	v_or_b32_e32 v162, 0x14000, v166
	v_add_u32_e32 v163, 0x14400, v166
	ds_read_b128 v[180:183], v162
	ds_read_b128 v[184:187], v163
	v_add_u32_e32 v162, 0x14800, v166
	v_add_u32_e32 v163, 0x14c00, v166
	ds_read_b128 v[188:191], v162
	ds_read_b128 v[210:213], v163
	s_add_u32 s16, s14, 0xfffc0080
	s_addc_u32 s17, s15, -1
	s_cmp_eq_u32 s53, 12
	s_cselect_b32 s19, s7, s17
	s_cselect_b32 s18, s49, s16
	s_cselect_b32 s17, s5, s52
	s_cselect_b32 s16, s50, s51
	s_mov_b32 m0, s43
	v_lshl_add_u64 v[162:163], s[14:15], 0, v[136:137]
	ds_read_b128 v[214:217], v165
	ds_read_b128 v[218:221], v165 offset:1024
	ds_read_b128 v[222:225], v165 offset:2048
	ds_read_b128 v[226:229], v165 offset:3072
	ds_read_b128 v[230:233], v165 offset:4096
	ds_read_b128 v[234:237], v165 offset:5120
	ds_read_b128 v[238:241], v165 offset:6144
	ds_read_b128 v[242:245], v165 offset:7168
	global_load_lds_dwordx4 v[162:163], off
	v_lshl_add_u64 v[162:163], s[14:15], 0, v[138:139]
	s_mov_b32 m0, s44
	s_nop 0
	global_load_lds_dwordx4 v[162:163], off
	s_waitcnt vmcnt(8)
	s_waitcnt lgkmcnt(0)
	s_barrier
	s_setprio 1
	s_waitcnt lgkmcnt(0)
	v_mfma_f32_16x16x32_bf16 v[124:127], v[140:143], v[214:217], 0
	v_mfma_f32_16x16x32_bf16 v[116:119], v[172:175], v[214:217], 0
	v_mfma_f32_16x16x32_bf16 v[108:111], v[140:143], v[222:225], 0
	v_mfma_f32_16x16x32_bf16 v[100:103], v[172:175], v[222:225], 0
	v_mfma_f32_16x16x32_bf16 v[92:95], v[140:143], v[230:233], 0
	v_mfma_f32_16x16x32_bf16 v[84:87], v[172:175], v[230:233], 0
	v_mfma_f32_16x16x32_bf16 v[76:79], v[140:143], v[238:241], 0
	v_mfma_f32_16x16x32_bf16 v[68:71], v[172:175], v[238:241], 0
	v_mfma_f32_16x16x32_bf16 v[124:127], v[168:171], v[218:221], v[124:127]
	v_mfma_f32_16x16x32_bf16 v[116:119], v[176:179], v[218:221], v[116:119]
	v_mfma_f32_16x16x32_bf16 v[108:111], v[168:171], v[226:229], v[108:111]
	v_mfma_f32_16x16x32_bf16 v[100:103], v[176:179], v[226:229], v[100:103]
	v_mfma_f32_16x16x32_bf16 v[92:95], v[168:171], v[234:237], v[92:95]
	v_mfma_f32_16x16x32_bf16 v[84:87], v[176:179], v[234:237], v[84:87]
	v_mfma_f32_16x16x32_bf16 v[76:79], v[168:171], v[242:245], v[76:79]
	v_mfma_f32_16x16x32_bf16 v[68:71], v[176:179], v[242:245], v[68:71]
	s_setprio 0
	s_setprio 1
	v_mfma_f32_16x16x32_bf16 v[120:123], v[180:183], v[214:217], 0
	v_mfma_f32_16x16x32_bf16 v[112:115], v[188:191], v[214:217], 0
	v_mfma_f32_16x16x32_bf16 v[104:107], v[180:183], v[222:225], 0
	v_mfma_f32_16x16x32_bf16 v[96:99], v[188:191], v[222:225], 0
	v_mfma_f32_16x16x32_bf16 v[88:91], v[180:183], v[230:233], 0
	v_mfma_f32_16x16x32_bf16 v[80:83], v[188:191], v[230:233], 0
	v_mfma_f32_16x16x32_bf16 v[72:75], v[180:183], v[238:241], 0
	v_mfma_f32_16x16x32_bf16 v[64:67], v[188:191], v[238:241], 0
	v_mfma_f32_16x16x32_bf16 v[120:123], v[184:187], v[218:221], v[120:123]
	v_mfma_f32_16x16x32_bf16 v[112:115], v[210:213], v[218:221], v[112:115]
	v_mfma_f32_16x16x32_bf16 v[104:107], v[184:187], v[226:229], v[104:107]
	v_mfma_f32_16x16x32_bf16 v[96:99], v[210:213], v[226:229], v[96:99]
	v_mfma_f32_16x16x32_bf16 v[88:91], v[184:187], v[234:237], v[88:91]
	v_mfma_f32_16x16x32_bf16 v[80:83], v[210:213], v[234:237], v[80:83]
	v_mfma_f32_16x16x32_bf16 v[72:75], v[184:187], v[242:245], v[72:75]
	v_mfma_f32_16x16x32_bf16 v[64:67], v[210:213], v[242:245], v[64:67]
	s_setprio 0
	s_barrier
	s_mov_b32 m0, s27
	v_lshl_add_u64 v[162:163], s[16:17], 0, v[132:133]
	s_add_u32 s54, s16, 0x40000
	ds_read_b128 v[214:217], v165 offset:16384
	ds_read_b128 v[218:221], v165 offset:17408
	ds_read_b128 v[222:225], v165 offset:18432
	ds_read_b128 v[226:229], v165 offset:19456
	ds_read_b128 v[230:233], v165 offset:20480
	ds_read_b128 v[234:237], v165 offset:21504
	ds_read_b128 v[238:241], v165 offset:22528
	ds_read_b128 v[242:245], v165 offset:23552
	global_load_lds_dwordx4 v[162:163], off
	v_lshl_add_u64 v[246:247], s[16:17], 0, v[128:129]
	s_mov_b32 m0, s28
	s_addc_u32 s55, s17, 0
	global_load_lds_dwordx4 v[246:247], off
	v_lshl_add_u64 v[248:249], s[54:55], 0, v[132:133]
	s_mov_b32 m0, s29
	v_lshl_add_u64 v[250:251], s[18:19], 0, v[130:131]
	global_load_lds_dwordx4 v[248:249], off
	v_lshl_add_u64 v[248:249], s[54:55], 0, v[128:129]
	s_mov_b32 m0, s30
	s_nop 0
	global_load_lds_dwordx4 v[248:249], off
	v_lshl_add_u64 v[248:249], s[18:19], 0, v[134:135]
	s_mov_b32 m0, s22
	s_nop 0
	global_load_lds_dwordx4 v[248:249], off
	s_mov_b32 m0, s31
	s_nop 0
	global_load_lds_dwordx4 v[250:251], off
	s_waitcnt vmcnt(8)
	s_waitcnt lgkmcnt(0)
	s_barrier
; #define PG8_STAGE(bufoff, gbase, voff) do { _Pragma("unroll") for (int _i = 0; _i < 2; ++_i) \
;         __builtin_amdgcn_global_load_lds((const unsigned*)((const char*)(gbase) + (voff)[_i]), (PG8_LAS unsigned*)(lds + (bufoff) + ldsw + _i * 8192), 16, 0, 0); } while (0)
; #define PG8_LDA(dst, b, h) do { _Pragma("unroll") for (int m = 0; m < 4; ++m) _Pragma("unroll") for (int k = 0; k < 2; ++k) dst[m][k] = *(const PG8_LAS bf16x8*)(lds + PG8_SA(b, h) + aoff + m * 2048 + k * 1024); } while (0)
; #define PG8_LDB(dst, b, h) do { _Pragma("unroll") for (int n = 0; n < 2; ++n) _Pragma("unroll") for (int k = 0; k < 2; ++k) dst[n][k] = *(const PG8_LAS bf16x8*)(lds + PG8_SB(b, h) + boff + n * 2048 + k * 1024); } while (0)
; #define PG8_MMA(ai, bj, At, Bt) do { __builtin_amdgcn_s_setprio(1); _Pragma("unroll") for (int m = 0; m < 4; ++m) _Pragma("unroll") for (int n = 0; n < 2; ++n) _Pragma("unroll") for (int k = 0; k < 2; ++k) \
;         acc[ai][bj][m][n] = __builtin_amdgcn_mfma_f32_16x16x32_bf16(Bt[n][k], At[m][k], acc[ai][bj][m][n], 0, 0, 0); __builtin_amdgcn_s_setprio(0); } while (0)
; #define PG8_WAIT_V(n) asm volatile("s_waitcnt vmcnt(" #n ")" ::: "memory")
; #define PG8_WAIT_L(n) asm volatile("s_waitcnt lgkmcnt(" #n ")" ::: "memory")
; #define PG8_BAR __builtin_amdgcn_s_barrier()
; #define PG8_SCHED __builtin_amdgcn_sched_barrier(0)
; template <class Epi, class Sched, bool ALIGN_EPI = false, bool SP2 = false>
; __device__ __forceinline__ void gemm_phase(PG8_LAS unsigned char* lds, const Gemm g, const Sched& S, const Epi& E) {
;     ...
;             PG8_WAIT_V(8); PG8_WAIT_L(0); PG8_BAR; PG8_MMA(1, 0, At, B0); PG8_MMA(1, 1, At, B1); PG8_BAR; PG8_SCHED;
;             PG8_LDB(B0, 1, 0); PG8_LDB(B1, 1, 1); PG8_SCHED; PG8_LDA(At, 1, 0); PG8_STAGE(PG8_SA(0, 1), a2 + hstep, voffA);
;             PG8_WAIT_V(8); PG8_WAIT_L(0); PG8_BAR; PG8_MMA(0, 0, At, B0); PG8_MMA(0, 1, At, B1); PG8_BAR; PG8_SCHED;
	s_setprio 1
	s_waitcnt lgkmcnt(0)
	v_mfma_f32_16x16x32_bf16 v[60:63], v[140:143], v[214:217], 0
	v_mfma_f32_16x16x32_bf16 v[52:55], v[172:175], v[214:217], 0
	v_mfma_f32_16x16x32_bf16 v[44:47], v[140:143], v[222:225], 0
	v_mfma_f32_16x16x32_bf16 v[36:39], v[172:175], v[222:225], 0
	v_mfma_f32_16x16x32_bf16 v[28:31], v[140:143], v[230:233], 0
	v_mfma_f32_16x16x32_bf16 v[20:23], v[172:175], v[230:233], 0
	v_mfma_f32_16x16x32_bf16 v[12:15], v[140:143], v[238:241], 0
	v_mfma_f32_16x16x32_bf16 v[4:7], v[172:175], v[238:241], 0
	v_mfma_f32_16x16x32_bf16 v[60:63], v[168:171], v[218:221], v[60:63]
	v_mfma_f32_16x16x32_bf16 v[52:55], v[176:179], v[218:221], v[52:55]
	v_mfma_f32_16x16x32_bf16 v[44:47], v[168:171], v[226:229], v[44:47]
	v_mfma_f32_16x16x32_bf16 v[36:39], v[176:179], v[226:229], v[36:39]
	v_mfma_f32_16x16x32_bf16 v[28:31], v[168:171], v[234:237], v[28:31]
	v_mfma_f32_16x16x32_bf16 v[20:23], v[176:179], v[234:237], v[20:23]
	v_mfma_f32_16x16x32_bf16 v[12:15], v[168:171], v[242:245], v[12:15]
	v_mfma_f32_16x16x32_bf16 v[4:7], v[176:179], v[242:245], v[4:7]
	s_setprio 0
	s_setprio 1
	v_mfma_f32_16x16x32_bf16 v[56:59], v[180:183], v[214:217], 0
	v_mfma_f32_16x16x32_bf16 v[48:51], v[188:191], v[214:217], 0
	v_mfma_f32_16x16x32_bf16 v[40:43], v[180:183], v[222:225], 0
	v_mfma_f32_16x16x32_bf16 v[32:35], v[188:191], v[222:225], 0
	v_mfma_f32_16x16x32_bf16 v[24:27], v[180:183], v[230:233], 0
	v_mfma_f32_16x16x32_bf16 v[16:19], v[188:191], v[230:233], 0
	v_mfma_f32_16x16x32_bf16 v[8:11], v[180:183], v[238:241], 0
	v_mfma_f32_16x16x32_bf16 v[0:3], v[188:191], v[238:241], 0
	v_mfma_f32_16x16x32_bf16 v[56:59], v[184:187], v[218:221], v[56:59]
	v_mfma_f32_16x16x32_bf16 v[48:51], v[210:213], v[218:221], v[48:51]
	v_mfma_f32_16x16x32_bf16 v[40:43], v[184:187], v[226:229], v[40:43]
	v_mfma_f32_16x16x32_bf16 v[32:35], v[210:213], v[226:229], v[32:35]
	v_mfma_f32_16x16x32_bf16 v[24:27], v[184:187], v[234:237], v[24:27]
	v_mfma_f32_16x16x32_bf16 v[16:19], v[210:213], v[234:237], v[16:19]
	v_mfma_f32_16x16x32_bf16 v[8:11], v[184:187], v[242:245], v[8:11]
	v_mfma_f32_16x16x32_bf16 v[0:3], v[210:213], v[242:245], v[0:3]
	s_setprio 0
	s_barrier
	v_or_b32_e32 v140, 0x18000, v166
	v_add_u32_e32 v167, 0x18400, v166
	ds_read_b128 v[140:143], v140
	ds_read_b128 v[168:171], v167
	v_add_u32_e32 v167, 0x18800, v166
	v_add_u32_e32 v176, 0x18c00, v166
	ds_read_b128 v[172:175], v167
	ds_read_b128 v[176:179], v176
	v_or_b32_e32 v167, 0x1c000, v166
	v_add_u32_e32 v184, 0x1c400, v166
	ds_read_b128 v[180:183], v167
	ds_read_b128 v[184:187], v184
	v_add_u32_e32 v167, 0x1c800, v166
	v_add_u32_e32 v208, 0x1cc00, v166
	ds_read_b128 v[188:191], v167
	ds_read_b128 v[210:213], v208
	s_add_u32 s18, s18, 0x40000
	s_addc_u32 s19, s19, 0
	s_mov_b32 m0, s33
	v_lshl_add_u64 v[208:209], s[18:19], 0, v[134:135]
	ds_read_b128 v[214:217], v165 offset:32768
	ds_read_b128 v[218:221], v165 offset:33792
	ds_read_b128 v[222:225], v165 offset:34816
	ds_read_b128 v[226:229], v165 offset:35840
	ds_read_b128 v[230:233], v165 offset:36864
	ds_read_b128 v[234:237], v165 offset:37888
	ds_read_b128 v[238:241], v165 offset:38912
	ds_read_b128 v[242:245], v165 offset:39936
	global_load_lds_dwordx4 v[208:209], off
	v_lshl_add_u64 v[208:209], s[18:19], 0, v[130:131]
	s_mov_b32 m0, s34
	s_nop 0
	global_load_lds_dwordx4 v[208:209], off
	s_waitcnt vmcnt(8)
	s_waitcnt lgkmcnt(0)
	s_barrier
	s_setprio 1
	s_waitcnt lgkmcnt(0)
	v_mfma_f32_16x16x32_bf16 v[124:127], v[140:143], v[214:217], v[124:127]
	v_mfma_f32_16x16x32_bf16 v[116:119], v[172:175], v[214:217], v[116:119]
	v_mfma_f32_16x16x32_bf16 v[108:111], v[140:143], v[222:225], v[108:111]
	v_mfma_f32_16x16x32_bf16 v[100:103], v[172:175], v[222:225], v[100:103]
	v_mfma_f32_16x16x32_bf16 v[92:95], v[140:143], v[230:233], v[92:95]
	v_mfma_f32_16x16x32_bf16 v[84:87], v[172:175], v[230:233], v[84:87]
	v_mfma_f32_16x16x32_bf16 v[76:79], v[140:143], v[238:241], v[76:79]
	v_mfma_f32_16x16x32_bf16 v[68:71], v[172:175], v[238:241], v[68:71]
	v_mfma_f32_16x16x32_bf16 v[124:127], v[168:171], v[218:221], v[124:127]
	v_mfma_f32_16x16x32_bf16 v[116:119], v[176:179], v[218:221], v[116:119]
	v_mfma_f32_16x16x32_bf16 v[108:111], v[168:171], v[226:229], v[108:111]
	v_mfma_f32_16x16x32_bf16 v[100:103], v[176:179], v[226:229], v[100:103]
	v_mfma_f32_16x16x32_bf16 v[92:95], v[168:171], v[234:237], v[92:95]
	v_mfma_f32_16x16x32_bf16 v[84:87], v[176:179], v[234:237], v[84:87]
	v_mfma_f32_16x16x32_bf16 v[76:79], v[168:171], v[242:245], v[76:79]
	v_mfma_f32_16x16x32_bf16 v[68:71], v[176:179], v[242:245], v[68:71]
	s_setprio 0
	s_setprio 1
	v_mfma_f32_16x16x32_bf16 v[120:123], v[180:183], v[214:217], v[120:123]
	v_mfma_f32_16x16x32_bf16 v[112:115], v[188:191], v[214:217], v[112:115]
	v_mfma_f32_16x16x32_bf16 v[104:107], v[180:183], v[222:225], v[104:107]
	v_mfma_f32_16x16x32_bf16 v[96:99], v[188:191], v[222:225], v[96:99]
	v_mfma_f32_16x16x32_bf16 v[88:91], v[180:183], v[230:233], v[88:91]
	v_mfma_f32_16x16x32_bf16 v[80:83], v[188:191], v[230:233], v[80:83]
	v_mfma_f32_16x16x32_bf16 v[72:75], v[180:183], v[238:241], v[72:75]
	v_mfma_f32_16x16x32_bf16 v[64:67], v[188:191], v[238:241], v[64:67]
	v_mfma_f32_16x16x32_bf16 v[120:123], v[184:187], v[218:221], v[120:123]
	v_mfma_f32_16x16x32_bf16 v[112:115], v[210:213], v[218:221], v[112:115]
	v_mfma_f32_16x16x32_bf16 v[104:107], v[184:187], v[226:229], v[104:107]
	v_mfma_f32_16x16x32_bf16 v[96:99], v[210:213], v[226:229], v[96:99]
	v_mfma_f32_16x16x32_bf16 v[88:91], v[184:187], v[234:237], v[88:91]
	v_mfma_f32_16x16x32_bf16 v[80:83], v[210:213], v[234:237], v[80:83]
	v_mfma_f32_16x16x32_bf16 v[72:75], v[184:187], v[242:245], v[72:75]
	v_mfma_f32_16x16x32_bf16 v[64:67], v[210:213], v[242:245], v[64:67]
	s_setprio 0
	s_barrier
; #define PG8_STAGE(bufoff, gbase, voff) do { _Pragma("unroll") for (int _i = 0; _i < 2; ++_i) \
;         __builtin_amdgcn_global_load_lds((const unsigned*)((const char*)(gbase) + (voff)[_i]), (PG8_LAS unsigned*)(lds + (bufoff) + ldsw + _i * 8192), 16, 0, 0); } while (0)
; #define PG8_LDA(dst, b, h) do { _Pragma("unroll") for (int m = 0; m < 4; ++m) _Pragma("unroll") for (int k = 0; k < 2; ++k) dst[m][k] = *(const PG8_LAS bf16x8*)(lds + PG8_SA(b, h) + aoff + m * 2048 + k * 1024); } while (0)
; #define PG8_MMA(ai, bj, At, Bt) do { __builtin_amdgcn_s_setprio(1); _Pragma("unroll") for (int m = 0; m < 4; ++m) _Pragma("unroll") for (int n = 0; n < 2; ++n) _Pragma("unroll") for (int k = 0; k < 2; ++k) \
;         acc[ai][bj][m][n] = __builtin_amdgcn_mfma_f32_16x16x32_bf16(Bt[n][k], At[m][k], acc[ai][bj][m][n], 0, 0, 0); __builtin_amdgcn_s_setprio(0); } while (0)
; #define PG8_WAIT_V(n) asm volatile("s_waitcnt vmcnt(" #n ")" ::: "memory")
; #define PG8_WAIT_L(n) asm volatile("s_waitcnt lgkmcnt(" #n ")" ::: "memory")
; #define PG8_BAR __builtin_amdgcn_s_barrier()
; #define PG8_SCHED __builtin_amdgcn_sched_barrier(0)
; template <class Epi, class Sched, bool ALIGN_EPI = false, bool SP2 = false>
; __device__ __forceinline__ void gemm_phase(PG8_LAS unsigned char* lds, const Gemm g, const Sched& S, const Epi& E) {
;     ...
;             PG8_WAIT_V(8); PG8_WAIT_L(0); PG8_BAR; PG8_MMA(0, 0, At, B0); PG8_MMA(0, 1, At, B1); PG8_BAR; PG8_SCHED;
;             PG8_LDA(At, 1, 1); PG8_STAGE(PG8_SB(1, 0), b3, voffB); PG8_STAGE(PG8_SB(1, 1), b3 + hstep, voffB); PG8_STAGE(PG8_SA(1, 0), a3, voffA);
;             PG8_WAIT_V(8); PG8_WAIT_L(0); PG8_BAR; PG8_MMA(1, 0, At, B0); PG8_MMA(1, 1, At, B1); PG8_BAR; PG8_SCHED;
	s_mov_b32 m0, s37
	v_lshl_add_u64 v[162:163], v[162:163], 0, s[94:95]
	s_add_u32 s16, s16, 0x40080
	ds_read_b128 v[214:217], v165 offset:49152
	ds_read_b128 v[218:221], v165 offset:50176
	ds_read_b128 v[222:225], v165 offset:51200
	ds_read_b128 v[226:229], v165 offset:52224
	ds_read_b128 v[230:233], v165 offset:53248
	ds_read_b128 v[234:237], v165 offset:54272
	ds_read_b128 v[238:241], v165 offset:55296
	ds_read_b128 v[242:245], v165 offset:56320
	global_load_lds_dwordx4 v[162:163], off
	v_lshl_add_u64 v[162:163], v[246:247], 0, s[94:95]
	s_mov_b32 m0, s38
	s_addc_u32 s17, s17, 0
	global_load_lds_dwordx4 v[162:163], off
	v_lshl_add_u64 v[162:163], s[16:17], 0, v[132:133]
	s_mov_b32 m0, s41
	s_nop 0
	global_load_lds_dwordx4 v[162:163], off
	v_lshl_add_u64 v[162:163], s[16:17], 0, v[128:129]
	s_mov_b32 m0, s42
	s_nop 0
	global_load_lds_dwordx4 v[162:163], off
	v_lshl_add_u64 v[162:163], v[248:249], 0, s[94:95]
	s_mov_b32 m0, s39
	s_nop 0
	global_load_lds_dwordx4 v[162:163], off
	v_lshl_add_u64 v[162:163], v[250:251], 0, s[94:95]
	s_mov_b32 m0, s40
	s_nop 0
	global_load_lds_dwordx4 v[162:163], off
	s_waitcnt vmcnt(8)
	s_waitcnt lgkmcnt(0)
	s_barrier
	s_setprio 1
	s_waitcnt lgkmcnt(0)
	v_mfma_f32_16x16x32_bf16 v[60:63], v[140:143], v[214:217], v[60:63]
	v_mfma_f32_16x16x32_bf16 v[52:55], v[172:175], v[214:217], v[52:55]
	v_mfma_f32_16x16x32_bf16 v[44:47], v[140:143], v[222:225], v[44:47]
	v_mfma_f32_16x16x32_bf16 v[36:39], v[172:175], v[222:225], v[36:39]
	v_mfma_f32_16x16x32_bf16 v[28:31], v[140:143], v[230:233], v[28:31]
	v_mfma_f32_16x16x32_bf16 v[20:23], v[172:175], v[230:233], v[20:23]
	v_mfma_f32_16x16x32_bf16 v[12:15], v[140:143], v[238:241], v[12:15]
	v_mfma_f32_16x16x32_bf16 v[4:7], v[172:175], v[238:241], v[4:7]
	v_mfma_f32_16x16x32_bf16 v[60:63], v[168:171], v[218:221], v[60:63]
	v_mfma_f32_16x16x32_bf16 v[52:55], v[176:179], v[218:221], v[52:55]
	v_mfma_f32_16x16x32_bf16 v[44:47], v[168:171], v[226:229], v[44:47]
	v_mfma_f32_16x16x32_bf16 v[36:39], v[176:179], v[226:229], v[36:39]
	v_mfma_f32_16x16x32_bf16 v[28:31], v[168:171], v[234:237], v[28:31]
	v_mfma_f32_16x16x32_bf16 v[20:23], v[176:179], v[234:237], v[20:23]
	v_mfma_f32_16x16x32_bf16 v[12:15], v[168:171], v[242:245], v[12:15]
	v_mfma_f32_16x16x32_bf16 v[4:7], v[176:179], v[242:245], v[4:7]
	s_setprio 0
	s_setprio 1
	v_mfma_f32_16x16x32_bf16 v[56:59], v[180:183], v[214:217], v[56:59]
	v_mfma_f32_16x16x32_bf16 v[48:51], v[188:191], v[214:217], v[48:51]
	v_mfma_f32_16x16x32_bf16 v[40:43], v[180:183], v[222:225], v[40:43]
	v_mfma_f32_16x16x32_bf16 v[32:35], v[188:191], v[222:225], v[32:35]
	v_mfma_f32_16x16x32_bf16 v[24:27], v[180:183], v[230:233], v[24:27]
	v_mfma_f32_16x16x32_bf16 v[16:19], v[188:191], v[230:233], v[16:19]
	v_mfma_f32_16x16x32_bf16 v[8:11], v[180:183], v[238:241], v[8:11]
	v_mfma_f32_16x16x32_bf16 v[0:3], v[188:191], v[238:241], v[0:3]
	v_mfma_f32_16x16x32_bf16 v[56:59], v[184:187], v[218:221], v[56:59]
	v_mfma_f32_16x16x32_bf16 v[48:51], v[210:213], v[218:221], v[48:51]
	v_mfma_f32_16x16x32_bf16 v[40:43], v[184:187], v[226:229], v[40:43]
	v_mfma_f32_16x16x32_bf16 v[32:35], v[210:213], v[226:229], v[32:35]
	v_mfma_f32_16x16x32_bf16 v[24:27], v[184:187], v[234:237], v[24:27]
	v_mfma_f32_16x16x32_bf16 v[16:19], v[210:213], v[234:237], v[16:19]
	v_mfma_f32_16x16x32_bf16 v[8:11], v[184:187], v[242:245], v[8:11]
	v_mfma_f32_16x16x32_bf16 v[0:3], v[210:213], v[242:245], v[0:3]
	s_setprio 0
	s_barrier
	s_add_i32 s53, s53, 2
	s_add_u32 s14, s14, 0x100
	s_addc_u32 s15, s15, 0
	s_add_u32 s51, s51, 0x100
	s_addc_u32 s52, s52, 0
